# FoX epilogue: SiLU-gate rows 1-3 are touch-prefetched together with row 0 so the serialized load-wait ladder hits cache
# speedup vs baseline: 1.0030x; 1.0030x over previous
; __device__ __forceinline__ u16 f2bf(float a) { return (u16)(pk2(a, 0.f) & 0xffffu); }
; __device__ __forceinline__ int a_crow(int r, int hi) { return (r & 3) + 8 * (r >> 2) + 4 * hi; }
; template <int MODE> ...
;     ...
;   if (hi == 0) wsf[32 + r32] = gate / l_reg;
;   asm volatile("s_waitcnt lgkmcnt(0)" ::: "memory");
;   float rli[16];
; #pragma unroll
;   for (int r = 0; r < 16; ++r) rli[r] = wsf[32 + a_crow(r, hi)];
; #pragma unroll
;   for (int r = 0; r < 16; ++r) { const int orow = a_crow(r, hi);
; #pragma unroll
;     for (int d0 = 0; d0 < 2; ++d0) stg[orow * 64 + d0 * 32 + r32] = f2bf(o[d0][r] * rli[r]); }
;   asm volatile("s_waitcnt lgkmcnt(0)\n\ts_barrier" ::: "memory");
; __device__ void pc2_phase(const Params& P, int layer, int chunk, char* smem, int* s_item, const int which) {
;     ...
; #pragma unroll
;       for (int i = 0; i < 4; i++) {
;         const int row = i * 8 + er;
;         const uint4 ov = *(const uint4*)(stg + row * 64 + ec);
;         const uint4 zz = *(const uint4*)(pb_ + (size_t)(q0w + row) * INC + C_ZB + head * 64 + ec);
.LBB0_293:
	s_or_b64 exec, exec, s[0:1]
	s_waitcnt lgkmcnt(0)
	ds_read_b128 v[34:37], v251 offset:49280
	v_lshlrev_b32_e32 v33, 13, v203
	v_lshl_or_b32 v50, v221, 1, v33
	v_lshl_add_u32 v50, v197, 1, v50
	ds_read_b128 v[38:41], v251 offset:49312
	ds_read_b128 v[42:45], v251 offset:49344
	ds_read_b128 v[46:49], v251 offset:49376
	s_waitcnt lgkmcnt(3)
	s_nop 0
	v_mul_f32_e32 v0, v0, v34
	v_cvt_pk_bf16_f32 v0, v0, s0
	ds_write_b16 v50, v0 offset:52288
	v_mul_f32_e32 v0, v17, v35
	v_cvt_pk_bf16_f32 v0, v0, s0
	ds_write_b16 v50, v0 offset:52352
	v_mul_f32_e32 v0, v1, v35
	v_cvt_pk_bf16_f32 v0, v0, s0
	ds_write_b16 v50, v0 offset:52416
	v_mul_f32_e32 v0, v18, v36
	v_cvt_pk_bf16_f32 v0, v0, s0
	ds_write_b16 v50, v0 offset:52480
	v_mul_f32_e32 v0, v2, v36
	v_cvt_pk_bf16_f32 v0, v0, s0
	ds_write_b16 v50, v0 offset:52544
	v_mul_f32_e32 v0, v19, v37
	v_cvt_pk_bf16_f32 v0, v0, s0
	ds_write_b16 v50, v0 offset:52608
	v_mul_f32_e32 v0, v3, v37
	v_cvt_pk_bf16_f32 v0, v0, s0
	ds_write_b16 v50, v0 offset:52672
	s_waitcnt lgkmcnt(9)
	v_mul_f32_e32 v0, v20, v38
	v_cvt_pk_bf16_f32 v0, v0, s0
	ds_write_b16 v50, v0 offset:53248
	v_mul_f32_e32 v0, v4, v38
	v_cvt_pk_bf16_f32 v0, v0, s0
	ds_write_b16 v50, v0 offset:53312
	v_mul_f32_e32 v0, v21, v39
	v_cvt_pk_bf16_f32 v0, v0, s0
	ds_write_b16 v50, v0 offset:53376
	v_mul_f32_e32 v0, v5, v39
	v_cvt_pk_bf16_f32 v0, v0, s0
	ds_write_b16 v50, v0 offset:53440
	v_mul_f32_e32 v0, v22, v40
	v_cvt_pk_bf16_f32 v0, v0, s0
	ds_write_b16 v50, v0 offset:53504
	v_mul_f32_e32 v0, v6, v40
	v_cvt_pk_bf16_f32 v0, v0, s0
	ds_write_b16 v50, v0 offset:53568
	v_mul_f32_e32 v0, v23, v41
	v_cvt_pk_bf16_f32 v0, v0, s0
	ds_write_b16 v50, v0 offset:53632
	v_mul_f32_e32 v0, v7, v41
	v_cvt_pk_bf16_f32 v0, v0, s0
	ds_write_b16 v50, v0 offset:53696
	s_waitcnt lgkmcnt(14)
	v_mul_f32_e32 v0, v24, v42
	v_cvt_pk_bf16_f32 v0, v0, s0
	ds_write_b16 v50, v0 offset:54272
	v_mul_f32_e32 v0, v8, v42
	v_cvt_pk_bf16_f32 v0, v0, s0
	ds_write_b16 v50, v0 offset:54336
	v_mul_f32_e32 v0, v25, v43
	v_cvt_pk_bf16_f32 v0, v0, s0
	ds_write_b16 v50, v0 offset:54400
	v_mul_f32_e32 v0, v9, v43
	v_cvt_pk_bf16_f32 v0, v0, s0
	ds_write_b16 v50, v0 offset:54464
	v_mul_f32_e32 v0, v26, v44
	v_cvt_pk_bf16_f32 v0, v0, s0
	ds_write_b16 v50, v0 offset:54528
	v_mul_f32_e32 v0, v10, v44
	v_cvt_pk_bf16_f32 v0, v0, s0
	ds_write_b16 v50, v0 offset:54592
	v_mul_f32_e32 v0, v27, v45
	v_cvt_pk_bf16_f32 v0, v0, s0
	ds_write_b16 v50, v0 offset:54656
	v_mul_f32_e32 v0, v11, v45
	v_cvt_pk_bf16_f32 v0, v0, s0
	ds_write_b16 v50, v0 offset:54720
	v_mul_f32_e32 v0, v28, v46
	v_cvt_pk_bf16_f32 v0, v0, s0
	ds_write_b16 v50, v0 offset:55296
	v_mul_f32_e32 v0, v12, v46
	v_cvt_pk_bf16_f32 v0, v0, s0
	ds_write_b16 v50, v0 offset:55360
	v_mul_f32_e32 v0, v29, v47
	v_cvt_pk_bf16_f32 v0, v0, s0
	ds_write_b16 v50, v0 offset:55424
	v_mul_f32_e32 v0, v13, v47
	v_cvt_pk_bf16_f32 v0, v0, s0
	ds_write_b16 v50, v0 offset:55488
	v_mul_f32_e32 v0, v30, v48
	v_cvt_pk_bf16_f32 v0, v0, s0
	ds_write_b16 v50, v0 offset:55552
	v_mul_f32_e32 v0, v14, v48
	v_cvt_pk_bf16_f32 v0, v0, s0
	ds_write_b16 v50, v0 offset:55616
	v_mul_f32_e32 v0, v31, v49
	v_cvt_pk_bf16_f32 v0, v0, s0
	ds_write_b16 v50, v0 offset:55680
	v_mul_f32_e32 v0, v15, v49
	v_cvt_pk_bf16_f32 v0, v0, s0
	v_bfe_u32 v32, v199, 3, 3
	ds_write_b16 v50, v0 offset:55744
	v_lshlrev_b32_e32 v0, 1, v201
	v_mul_f32_e32 v16, v16, v34
	v_and_b32_e32 v96, 0x70, v0
	v_or_b32_e32 v0, v206, v32
	v_mov_b64_e32 v[2:3], s[8:9]
	s_movk_i32 s7, 0x4680
	v_readlane_b32 s8, v253, 34
	v_cvt_pk_bf16_f32 v16, v16, s0
	v_mad_i64_i32 v[0:1], s[0:1], v0, s7, v[2:3]
	v_readlane_b32 s9, v253, 35
	s_movk_i32 s6, 0x2000
	ds_write_b16 v50, v16 offset:52224
	v_lshl_add_u64 v[0:1], v[0:1], 0, s[8:9]
	v_lshl_add_u64 v[0:1], v[0:1], 0, v[96:97]
	v_add_co_u32_e32 v0, vcc, s6, v0
	s_waitcnt lgkmcnt(0)
	s_barrier
	v_or_b32_e32 v18, v33, v96
	s_nop 0
	v_addc_co_u32_e32 v1, vcc, 0, v1, vcc
	global_load_dwordx4 v[4:7], v[0:1], off offset:3712
	s_mov_b64 s[100:101], 0x23400
	v_lshl_add_u64 v[112:113], v[0:1], 0, s[100:101]
	global_load_dwordx4 v[100:103], v[112:113], off offset:3712
	v_lshl_add_u64 v[112:113], v[112:113], 0, s[100:101]
	global_load_dwordx4 v[104:107], v[112:113], off offset:3712
	v_lshl_add_u64 v[112:113], v[112:113], 0, s[100:101]
	global_load_dwordx4 v[108:111], v[112:113], off offset:3712
	v_lshl_or_b32 v0, v32, 7, v18
	ds_read_b128 v[8:11], v0 offset:52224
	s_lshl_b64 s[0:1], s[2:3], 11
	v_readlane_b32 s44, v253, 44
	v_readlane_b32 s56, v253, 56
	v_readlane_b32 s57, v253, 57
	s_waitcnt lgkmcnt(0)
	v_lshlrev_b32_e32 v16, 16, v8
	v_and_b32_e32 v17, 0xffff0000, v8
	s_mov_b32 s37, 0x20000
	v_readlane_b32 s45, v253, 45
	v_readlane_b32 s46, v253, 46
	v_readlane_b32 s47, v253, 47
	v_readlane_b32 s48, v253, 48
	v_readlane_b32 s49, v253, 49
	v_readlane_b32 s50, v253, 50
	v_readlane_b32 s51, v253, 51
	v_readlane_b32 s52, v253, 52
	v_readlane_b32 s53, v253, 53
	v_readlane_b32 s54, v253, 54
	v_readlane_b32 s55, v253, 55
	v_readlane_b32 s58, v253, 58
	v_readlane_b32 s59, v253, 59
	s_waitcnt vmcnt(0)
; __device__ __forceinline__ float bflo(unsigned u) { return __uint_as_float(u << 16); }
; __device__ __forceinline__ float bfhi(unsigned u) { return __uint_as_float(u & 0xffff0000u); }
; __device__ __forceinline__ float siluf_(float x) { return x * __builtin_amdgcn_rcpf(1.f + __expf(-x)); }
; __device__ void pc2_phase(const Params& P, int layer, int chunk, char* smem, int* s_item, const int which) {
;     ...
; #pragma unroll
;       for (int i = 0; i < 4; i++) {
;         const int row = i * 8 + er;
;         const uint4 ov = *(const uint4*)(stg + row * 64 + ec);
;         const uint4 zz = *(const uint4*)(pb_ + (size_t)(q0w + row) * INC + C_ZB + head * 64 + ec);
;         uint4 y;
;         y.x = pk2(bflo(ov.x) * siluf_(bflo(zz.x)), bfhi(ov.x) * siluf_(bfhi(zz.x)));
;         y.y = pk2(bflo(ov.y) * siluf_(bflo(zz.y)), bfhi(ov.y) * siluf_(bfhi(zz.y)));
;         y.z = pk2(bflo(ov.z) * siluf_(bflo(zz.z)), bfhi(ov.z) * siluf_(bfhi(zz.z)));
;         y.w = pk2(bflo(ov.w) * siluf_(bflo(zz.w)), bfhi(ov.w) * siluf_(bfhi(zz.w)));
;         *(uint4*)(P.yb + (roww + row) * DM + head * 64 + ec) = y;
;       }
	v_lshlrev_b32_e32 v12, 16, v4
	v_and_b32_e32 v13, 0xffff0000, v4
	v_mul_f32_e32 v1, 0xbfb8aa3b, v12
	v_exp_f32_e32 v1, v1
	v_mul_f32_e32 v4, 0xbfb8aa3b, v13
	v_exp_f32_e32 v4, v4
	v_add_f32_e32 v0, 1.0, v1
	v_rcp_f32_e32 v14, v0
	v_add_f32_e32 v0, 1.0, v4
	v_rcp_f32_e32 v15, v0
	v_lshl_add_u64 v[0:1], s[0:1], 0, v[206:207]
	v_pk_mul_f32 v[12:13], v[14:15], v[12:13]
	v_lshlrev_b32_e32 v14, 16, v5
	v_and_b32_e32 v15, 0xffff0000, v5
	v_mul_f32_e32 v4, 0xbfb8aa3b, v14
	v_exp_f32_e32 v8, v4
	v_mul_f32_e32 v4, 0xbfb8aa3b, v15
	v_exp_f32_e32 v19, v4
	v_pk_mul_f32 v[4:5], v[12:13], v[16:17]
	v_add_f32_e32 v8, 1.0, v8
	v_rcp_f32_e32 v12, v8
	v_add_f32_e32 v8, 1.0, v19
	v_rcp_f32_e32 v13, v8
	v_cvt_pk_bf16_f32 v4, v4, v5
	v_lshlrev_b32_e32 v8, 16, v9
	v_and_b32_e32 v9, 0xffff0000, v9
	v_pk_mul_f32 v[12:13], v[12:13], v[14:15]
	v_lshlrev_b32_e32 v14, 16, v6
	v_and_b32_e32 v15, 0xffff0000, v6
	v_mul_f32_e32 v5, 0xbfb8aa3b, v14
	v_exp_f32_e32 v5, v5
	v_mul_f32_e32 v6, 0xbfb8aa3b, v15
	v_exp_f32_e32 v6, v6
	v_pk_mul_f32 v[8:9], v[12:13], v[8:9]
	v_add_f32_e32 v5, 1.0, v5
	v_rcp_f32_e32 v12, v5
	v_add_f32_e32 v5, 1.0, v6
	v_rcp_f32_e32 v13, v5
	v_cvt_pk_bf16_f32 v5, v8, v9
	v_lshlrev_b32_e32 v8, 16, v10
	v_and_b32_e32 v9, 0xffff0000, v10
	v_pk_mul_f32 v[12:13], v[12:13], v[14:15]
	v_lshlrev_b32_e32 v14, 16, v7
	v_and_b32_e32 v15, 0xffff0000, v7
	v_mul_f32_e32 v6, 0xbfb8aa3b, v14
	v_exp_f32_e32 v10, v6
	v_mul_f32_e32 v6, 0xbfb8aa3b, v15
	v_exp_f32_e32 v16, v6
	v_pk_mul_f32 v[6:7], v[12:13], v[8:9]
	v_add_f32_e32 v8, 1.0, v10
	v_rcp_f32_e32 v8, v8
	v_add_f32_e32 v9, 1.0, v16
	v_rcp_f32_e32 v9, v9
	v_lshlrev_b32_e32 v10, 16, v11
	v_and_b32_e32 v11, 0xffff0000, v11
	v_cvt_pk_bf16_f32 v6, v6, v7
	v_pk_mul_f32 v[8:9], v[8:9], v[14:15]
	v_or_b32_e32 v19, 8, v32
	v_pk_mul_f32 v[8:9], v[8:9], v[10:11]
	s_nop 0
	v_cvt_pk_bf16_f32 v7, v8, v9
	v_or_b32_e32 v8, v0, v32
	v_mov_b32_e32 v9, v1
	v_lshlrev_b64 v[8:9], 11, v[8:9]
	v_lshl_add_u64 v[8:9], s[56:57], 0, v[8:9]
	v_lshl_add_u64 v[8:9], v[8:9], 0, s[8:9]
	v_lshl_add_u64 v[8:9], v[8:9], 0, v[96:97]
	global_store_dwordx4 v[8:9], v[4:7], off
	v_lshl_or_b32 v8, v19, 7, v18
	s_nop 0
	v_or_b32_e32 v4, v206, v19
	v_mad_i64_i32 v[4:5], s[0:1], v4, s7, v[2:3]
	v_lshl_add_u64 v[4:5], v[4:5], 0, s[8:9]
	v_lshl_add_u64 v[4:5], v[4:5], 0, v[96:97]
	v_add_co_u32_e32 v4, vcc, s6, v4
	s_nop 1
	v_addc_co_u32_e32 v5, vcc, 0, v5, vcc
	global_load_dwordx4 v[4:7], v[4:5], off offset:3712
	s_waitcnt vmcnt(0)
	v_lshlrev_b32_e32 v12, 16, v4
	v_and_b32_e32 v13, 0xffff0000, v4
	v_mul_f32_e32 v4, 0xbfb8aa3b, v12
	v_exp_f32_e32 v4, v4
	v_mul_f32_e32 v9, 0xbfb8aa3b, v13
	v_exp_f32_e32 v15, v9
	ds_read_b128 v[8:11], v8 offset:52224
	v_add_f32_e32 v4, 1.0, v4
	v_rcp_f32_e32 v14, v4
	v_add_f32_e32 v4, 1.0, v15
	v_rcp_f32_e32 v15, v4
	s_waitcnt lgkmcnt(0)
	v_lshlrev_b32_e32 v16, 16, v8
	v_and_b32_e32 v17, 0xffff0000, v8
	v_pk_mul_f32 v[12:13], v[14:15], v[12:13]
	v_lshlrev_b32_e32 v14, 16, v5
	v_and_b32_e32 v15, 0xffff0000, v5
	v_mul_f32_e32 v4, 0xbfb8aa3b, v14
	v_exp_f32_e32 v8, v4
	v_mul_f32_e32 v4, 0xbfb8aa3b, v15
	v_exp_f32_e32 v20, v4
	v_pk_mul_f32 v[4:5], v[12:13], v[16:17]
	v_add_f32_e32 v8, 1.0, v8
	v_rcp_f32_e32 v12, v8
	v_add_f32_e32 v8, 1.0, v20
	v_rcp_f32_e32 v13, v8
	v_cvt_pk_bf16_f32 v4, v4, v5
	v_lshlrev_b32_e32 v8, 16, v9
	v_and_b32_e32 v9, 0xffff0000, v9
	v_pk_mul_f32 v[12:13], v[12:13], v[14:15]
	v_lshlrev_b32_e32 v14, 16, v6
	v_and_b32_e32 v15, 0xffff0000, v6
	v_mul_f32_e32 v5, 0xbfb8aa3b, v14
	v_exp_f32_e32 v5, v5
	v_mul_f32_e32 v6, 0xbfb8aa3b, v15
	v_exp_f32_e32 v6, v6
	v_pk_mul_f32 v[8:9], v[12:13], v[8:9]
	v_add_f32_e32 v5, 1.0, v5
	v_rcp_f32_e32 v12, v5
	v_add_f32_e32 v5, 1.0, v6
	v_rcp_f32_e32 v13, v5
	v_cvt_pk_bf16_f32 v5, v8, v9
	v_lshlrev_b32_e32 v8, 16, v10
	v_and_b32_e32 v9, 0xffff0000, v10
	v_pk_mul_f32 v[12:13], v[12:13], v[14:15]
	v_lshlrev_b32_e32 v14, 16, v7
	v_and_b32_e32 v15, 0xffff0000, v7
	v_mul_f32_e32 v6, 0xbfb8aa3b, v14
	v_exp_f32_e32 v10, v6
	v_mul_f32_e32 v6, 0xbfb8aa3b, v15
	v_exp_f32_e32 v16, v6
	v_pk_mul_f32 v[6:7], v[12:13], v[8:9]
	v_add_f32_e32 v8, 1.0, v10
	v_rcp_f32_e32 v8, v8
	v_add_f32_e32 v9, 1.0, v16
	v_rcp_f32_e32 v9, v9
	v_lshlrev_b32_e32 v10, 16, v11
	v_and_b32_e32 v11, 0xffff0000, v11
	v_cvt_pk_bf16_f32 v6, v6, v7
	v_pk_mul_f32 v[8:9], v[8:9], v[14:15]
	s_nop 0
	v_pk_mul_f32 v[8:9], v[8:9], v[10:11]
	s_nop 0
	v_cvt_pk_bf16_f32 v7, v8, v9
	v_or_b32_e32 v8, v0, v19
	v_mov_b32_e32 v9, v1
	v_lshlrev_b64 v[8:9], 11, v[8:9]
	v_lshl_add_u64 v[8:9], s[56:57], 0, v[8:9]
	v_lshl_add_u64 v[8:9], v[8:9], 0, s[8:9]
	v_lshl_add_u64 v[8:9], v[8:9], 0, v[96:97]
	v_or_b32_e32 v19, 16, v32
	global_store_dwordx4 v[8:9], v[4:7], off
	v_lshl_or_b32 v8, v19, 7, v18
	s_nop 0
	v_or_b32_e32 v4, v206, v19
	v_mad_i64_i32 v[4:5], s[0:1], v4, s7, v[2:3]
	v_lshl_add_u64 v[4:5], v[4:5], 0, s[8:9]
	v_lshl_add_u64 v[4:5], v[4:5], 0, v[96:97]
	v_add_co_u32_e32 v4, vcc, s6, v4
	s_nop 1
	v_addc_co_u32_e32 v5, vcc, 0, v5, vcc
	global_load_dwordx4 v[4:7], v[4:5], off offset:3712
	s_waitcnt vmcnt(0)
; __device__ __forceinline__ float bflo(unsigned u) { return __uint_as_float(u << 16); }
; __device__ __forceinline__ float bfhi(unsigned u) { return __uint_as_float(u & 0xffff0000u); }
; __device__ __forceinline__ float siluf_(float x) { return x * __builtin_amdgcn_rcpf(1.f + __expf(-x)); }
; __device__ void pc2_phase(const Params& P, int layer, int chunk, char* smem, int* s_item, const int which) {
;     ...
; #pragma unroll
;       for (int i = 0; i < 4; i++) {
;         const int row = i * 8 + er;
;         const uint4 ov = *(const uint4*)(stg + row * 64 + ec);
;         const uint4 zz = *(const uint4*)(pb_ + (size_t)(q0w + row) * INC + C_ZB + head * 64 + ec);
;         uint4 y;
;         y.x = pk2(bflo(ov.x) * siluf_(bflo(zz.x)), bfhi(ov.x) * siluf_(bfhi(zz.x)));
;         y.y = pk2(bflo(ov.y) * siluf_(bflo(zz.y)), bfhi(ov.y) * siluf_(bfhi(zz.y)));
;         y.z = pk2(bflo(ov.z) * siluf_(bflo(zz.z)), bfhi(ov.z) * siluf_(bfhi(zz.z)));
;         y.w = pk2(bflo(ov.w) * siluf_(bflo(zz.w)), bfhi(ov.w) * siluf_(bfhi(zz.w)));
;         *(uint4*)(P.yb + (roww + row) * DM + head * 64 + ec) = y;
;       }
	v_lshlrev_b32_e32 v12, 16, v4
	v_and_b32_e32 v13, 0xffff0000, v4
	v_mul_f32_e32 v4, 0xbfb8aa3b, v12
	v_exp_f32_e32 v4, v4
	v_mul_f32_e32 v9, 0xbfb8aa3b, v13
	v_exp_f32_e32 v15, v9
	ds_read_b128 v[8:11], v8 offset:52224
	v_add_f32_e32 v4, 1.0, v4
	v_rcp_f32_e32 v14, v4
	v_add_f32_e32 v4, 1.0, v15
	v_rcp_f32_e32 v15, v4
	s_waitcnt lgkmcnt(0)
	v_lshlrev_b32_e32 v16, 16, v8
	v_and_b32_e32 v17, 0xffff0000, v8
	v_pk_mul_f32 v[12:13], v[14:15], v[12:13]
	v_lshlrev_b32_e32 v14, 16, v5
	v_and_b32_e32 v15, 0xffff0000, v5
	v_mul_f32_e32 v4, 0xbfb8aa3b, v14
	v_exp_f32_e32 v8, v4
	v_mul_f32_e32 v4, 0xbfb8aa3b, v15
	v_exp_f32_e32 v20, v4
	v_pk_mul_f32 v[4:5], v[12:13], v[16:17]
	v_add_f32_e32 v8, 1.0, v8
	v_rcp_f32_e32 v12, v8
	v_add_f32_e32 v8, 1.0, v20
	v_rcp_f32_e32 v13, v8
	v_cvt_pk_bf16_f32 v4, v4, v5
	v_lshlrev_b32_e32 v8, 16, v9
	v_and_b32_e32 v9, 0xffff0000, v9
	v_pk_mul_f32 v[12:13], v[12:13], v[14:15]
	v_lshlrev_b32_e32 v14, 16, v6
	v_and_b32_e32 v15, 0xffff0000, v6
	v_mul_f32_e32 v5, 0xbfb8aa3b, v14
	v_exp_f32_e32 v5, v5
	v_mul_f32_e32 v6, 0xbfb8aa3b, v15
	v_exp_f32_e32 v6, v6
	v_pk_mul_f32 v[8:9], v[12:13], v[8:9]
	v_add_f32_e32 v5, 1.0, v5
	v_rcp_f32_e32 v12, v5
	v_add_f32_e32 v5, 1.0, v6
	v_rcp_f32_e32 v13, v5
	v_cvt_pk_bf16_f32 v5, v8, v9
	v_lshlrev_b32_e32 v8, 16, v10
	v_and_b32_e32 v9, 0xffff0000, v10
	v_pk_mul_f32 v[12:13], v[12:13], v[14:15]
	v_lshlrev_b32_e32 v14, 16, v7
	v_and_b32_e32 v15, 0xffff0000, v7
	v_mul_f32_e32 v6, 0xbfb8aa3b, v14
	v_exp_f32_e32 v10, v6
	v_mul_f32_e32 v6, 0xbfb8aa3b, v15
	v_exp_f32_e32 v16, v6
	v_pk_mul_f32 v[6:7], v[12:13], v[8:9]
	v_add_f32_e32 v8, 1.0, v10
	v_rcp_f32_e32 v8, v8
	v_add_f32_e32 v9, 1.0, v16
	v_rcp_f32_e32 v9, v9
	v_lshlrev_b32_e32 v10, 16, v11
	v_and_b32_e32 v11, 0xffff0000, v11
	v_cvt_pk_bf16_f32 v6, v6, v7
	v_pk_mul_f32 v[8:9], v[8:9], v[14:15]
	s_nop 0
	v_pk_mul_f32 v[8:9], v[8:9], v[10:11]
	s_nop 0
	v_cvt_pk_bf16_f32 v7, v8, v9
	v_or_b32_e32 v8, v0, v19
	v_mov_b32_e32 v9, v1
	v_lshlrev_b64 v[8:9], 11, v[8:9]
	v_lshl_add_u64 v[8:9], s[56:57], 0, v[8:9]
	v_lshl_add_u64 v[8:9], v[8:9], 0, s[8:9]
	v_lshl_add_u64 v[8:9], v[8:9], 0, v[96:97]
	v_or_b32_e32 v19, 24, v32
	global_store_dwordx4 v[8:9], v[4:7], off
	v_or_b32_e32 v0, v0, v19
	v_lshlrev_b64 v[0:1], 11, v[0:1]
	v_or_b32_e32 v4, v206, v19
	v_mad_i64_i32 v[2:3], s[0:1], v4, s7, v[2:3]
	v_lshl_add_u64 v[2:3], v[2:3], 0, s[8:9]
	v_lshl_add_u64 v[2:3], v[2:3], 0, v[96:97]
	v_add_co_u32_e32 v2, vcc, s6, v2
	v_lshl_or_b32 v6, v19, 7, v18
	s_nop 0
	v_addc_co_u32_e32 v3, vcc, 0, v3, vcc
	global_load_dwordx4 v[2:5], v[2:3], off offset:3712
	ds_read_b128 v[6:9], v6 offset:52224
	v_lshl_add_u64 v[0:1], s[56:57], 0, v[0:1]
	v_lshl_add_u64 v[0:1], v[0:1], 0, s[8:9]
	v_lshl_add_u64 v[0:1], v[0:1], 0, v[96:97]
	s_waitcnt lgkmcnt(0)
	v_lshlrev_b32_e32 v10, 16, v6
	v_and_b32_e32 v11, 0xffff0000, v6
	s_waitcnt vmcnt(0)
	v_lshlrev_b32_e32 v12, 16, v2
	v_and_b32_e32 v13, 0xffff0000, v2
	v_lshlrev_b32_e32 v14, 16, v3
	v_and_b32_e32 v15, 0xffff0000, v3
	v_mul_f32_e32 v2, 0xbfb8aa3b, v12
	v_mul_f32_e32 v3, 0xbfb8aa3b, v13
	v_exp_f32_e32 v2, v2
	v_exp_f32_e32 v3, v3
	v_mul_f32_e32 v6, 0xbfb8aa3b, v14
	v_mul_f32_e32 v16, 0xbfb8aa3b, v15
	v_add_f32_e32 v2, 1.0, v2
	v_add_f32_e32 v3, 1.0, v3
	v_rcp_f32_e32 v2, v2
	v_rcp_f32_e32 v3, v3
	v_exp_f32_e32 v6, v6
	v_exp_f32_e32 v16, v16
	v_pk_mul_f32 v[2:3], v[2:3], v[12:13]
	s_nop 0
	v_pk_mul_f32 v[2:3], v[2:3], v[10:11]
	v_lshlrev_b32_e32 v12, 16, v4
	v_add_f32_e32 v6, 1.0, v6
	v_add_f32_e32 v17, 1.0, v16
	v_cvt_pk_bf16_f32 v2, v2, v3
	v_and_b32_e32 v13, 0xffff0000, v4
	v_mul_f32_e32 v3, 0xbfb8aa3b, v12
	v_rcp_f32_e32 v16, v6
	v_rcp_f32_e32 v17, v17
	v_exp_f32_e32 v3, v3
	v_mul_f32_e32 v4, 0xbfb8aa3b, v13
	v_exp_f32_e32 v4, v4
	v_lshlrev_b32_e32 v6, 16, v7
	v_and_b32_e32 v7, 0xffff0000, v7
	v_pk_mul_f32 v[10:11], v[16:17], v[14:15]
	v_add_f32_e32 v3, 1.0, v3
	v_pk_mul_f32 v[6:7], v[10:11], v[6:7]
	v_rcp_f32_e32 v10, v3
	v_add_f32_e32 v3, 1.0, v4
	v_rcp_f32_e32 v11, v3
	v_cvt_pk_bf16_f32 v3, v6, v7
	v_lshlrev_b32_e32 v6, 16, v8
	v_and_b32_e32 v7, 0xffff0000, v8
	v_pk_mul_f32 v[10:11], v[10:11], v[12:13]
	v_lshlrev_b32_e32 v12, 16, v5
	v_and_b32_e32 v13, 0xffff0000, v5
	v_mul_f32_e32 v4, 0xbfb8aa3b, v12
	v_exp_f32_e32 v8, v4
	v_mul_f32_e32 v4, 0xbfb8aa3b, v13
	v_exp_f32_e32 v14, v4
	v_pk_mul_f32 v[4:5], v[10:11], v[6:7]
	v_add_f32_e32 v6, 1.0, v8
	v_rcp_f32_e32 v6, v6
	v_add_f32_e32 v7, 1.0, v14
	v_rcp_f32_e32 v7, v7
	v_lshlrev_b32_e32 v8, 16, v9
	v_and_b32_e32 v9, 0xffff0000, v9
	v_cvt_pk_bf16_f32 v4, v4, v5
	v_pk_mul_f32 v[6:7], v[6:7], v[12:13]
	s_nop 0
	v_pk_mul_f32 v[6:7], v[6:7], v[8:9]
	s_nop 0
	v_cvt_pk_bf16_f32 v5, v6, v7
	global_store_dwordx4 v[0:1], v[2:5], off
